# same as previous; carry-out of the SwiGLU address mad moved to s[24:25] (hazard hygiene)
# baseline (speedup 1.0000x reference)
.LBB0_736:
	v_mov_b32_e32 v140, v145
	s_mov_b32 s17, s79
	v_mov_b32_e32 v141, v144
	s_mov_b32 s19, s62
	s_lshl_b32 s24, s24, 8
	s_lshl_b32 s19, s19, 6
	s_add_i32 s19, s19, s24
	v_add_u32_e32 v148, s19, v141
	s_lshl_b32 s19, s25, 7
	s_lshl_b32 s17, s17, 4
	s_add_i32 s17, s17, s19
	v_lshl_add_u32 v142, v140, 2, s17
	v_ashrrev_i32_e32 v143, 31, v142
	v_mov_b64_e32 v[140:141], s[6:7]
	v_mad_i64_i32 v[150:151], s[24:25], v148, s47, v[140:141]
	v_lshlrev_b64 v[142:143], 1, v[142:143]
	v_lshl_add_u64 v[150:151], v[150:151], 0, v[142:143]
	s_andn2_b64 vcc, exec, s[2:3]
	v_mul_f32_e32 v152, 0xbfb8aa3b, v126
	v_mul_f32_e32 v153, 0xbfb8aa3b, v127
	v_mul_f32_e32 v154, 0xbfb8aa3b, v128
	v_mul_f32_e32 v155, 0xbfb8aa3b, v129
	v_mul_f32_e32 v156, 0xbfb8aa3b, v118
	v_mul_f32_e32 v157, 0xbfb8aa3b, v119
	v_mul_f32_e32 v158, 0xbfb8aa3b, v120
	v_mul_f32_e32 v159, 0xbfb8aa3b, v121
	v_exp_f32_e32 v152, v152
	v_exp_f32_e32 v153, v153
	v_exp_f32_e32 v154, v154
	v_exp_f32_e32 v155, v155
	v_exp_f32_e32 v156, v156
	v_exp_f32_e32 v157, v157
	v_exp_f32_e32 v158, v158
	v_exp_f32_e32 v159, v159
	v_add_f32_e32 v152, 1.0, v152
	v_add_f32_e32 v153, 1.0, v153
	v_add_f32_e32 v154, 1.0, v154
	v_add_f32_e32 v155, 1.0, v155
	v_add_f32_e32 v156, 1.0, v156
	v_add_f32_e32 v157, 1.0, v157
	v_add_f32_e32 v158, 1.0, v158
	v_add_f32_e32 v159, 1.0, v159
	v_rcp_f32_e32 v152, v152
	v_rcp_f32_e32 v153, v153
	v_rcp_f32_e32 v154, v154
	v_rcp_f32_e32 v155, v155
	v_rcp_f32_e32 v156, v156
	v_rcp_f32_e32 v157, v157
	v_rcp_f32_e32 v158, v158
	v_rcp_f32_e32 v159, v159
	v_mul_f32_e32 v152, v126, v152
	v_mul_f32_e32 v153, v127, v153
	v_mul_f32_e32 v154, v128, v154
	v_mul_f32_e32 v155, v129, v155
	v_mul_f32_e32 v156, v118, v156
	v_mul_f32_e32 v157, v119, v157
	v_mul_f32_e32 v158, v120, v158
	v_mul_f32_e32 v159, v121, v159
	v_mul_f32_e32 v122, v122, v152
	v_mul_f32_e32 v123, v123, v153
	v_mul_f32_e32 v124, v124, v154
	v_mul_f32_e32 v125, v125, v155
	v_mul_f32_e32 v114, v114, v156
	v_mul_f32_e32 v115, v115, v157
	v_mul_f32_e32 v116, v116, v158
	v_mul_f32_e32 v117, v117, v159
	v_cvt_pk_bf16_f32 v122, v122, v123
	v_cvt_pk_bf16_f32 v123, v124, v125
	v_cvt_pk_bf16_f32 v114, v114, v115
	v_cvt_pk_bf16_f32 v115, v116, v117
	v_mul_f32_e32 v152, 0xbfb8aa3b, v110
	v_mul_f32_e32 v153, 0xbfb8aa3b, v111
	v_mul_f32_e32 v154, 0xbfb8aa3b, v112
	v_mul_f32_e32 v155, 0xbfb8aa3b, v113
	v_mul_f32_e32 v156, 0xbfb8aa3b, v102
	v_mul_f32_e32 v157, 0xbfb8aa3b, v103
	v_mul_f32_e32 v158, 0xbfb8aa3b, v104
	v_mul_f32_e32 v159, 0xbfb8aa3b, v105
	v_exp_f32_e32 v152, v152
	v_exp_f32_e32 v153, v153
	v_exp_f32_e32 v154, v154
	v_exp_f32_e32 v155, v155
	v_exp_f32_e32 v156, v156
	v_exp_f32_e32 v157, v157
	v_exp_f32_e32 v158, v158
	v_exp_f32_e32 v159, v159
	v_add_f32_e32 v152, 1.0, v152
	v_add_f32_e32 v153, 1.0, v153
	v_add_f32_e32 v154, 1.0, v154
	v_add_f32_e32 v155, 1.0, v155
	v_add_f32_e32 v156, 1.0, v156
	v_add_f32_e32 v157, 1.0, v157
	v_add_f32_e32 v158, 1.0, v158
	v_add_f32_e32 v159, 1.0, v159
	v_rcp_f32_e32 v152, v152
	v_rcp_f32_e32 v153, v153
	v_rcp_f32_e32 v154, v154
	v_rcp_f32_e32 v155, v155
	v_rcp_f32_e32 v156, v156
	v_rcp_f32_e32 v157, v157
	v_rcp_f32_e32 v158, v158
	v_rcp_f32_e32 v159, v159
	v_mul_f32_e32 v152, v110, v152
	v_mul_f32_e32 v153, v111, v153
	v_mul_f32_e32 v154, v112, v154
	v_mul_f32_e32 v155, v113, v155
	v_mul_f32_e32 v156, v102, v156
	v_mul_f32_e32 v157, v103, v157
	v_mul_f32_e32 v158, v104, v158
	v_mul_f32_e32 v159, v105, v159
	v_mul_f32_e32 v106, v106, v152
	v_mul_f32_e32 v107, v107, v153
	v_mul_f32_e32 v108, v108, v154
	v_mul_f32_e32 v109, v109, v155
	v_mul_f32_e32 v98, v98, v156
	v_mul_f32_e32 v99, v99, v157
	v_mul_f32_e32 v100, v100, v158
	v_mul_f32_e32 v101, v101, v159
	v_cvt_pk_bf16_f32 v106, v106, v107
	v_cvt_pk_bf16_f32 v107, v108, v109
	v_cvt_pk_bf16_f32 v98, v98, v99
	v_cvt_pk_bf16_f32 v99, v100, v101
	v_and_b32_e32 v160, 7, v144
	v_lshlrev_b32_e32 v160, 1, v160
	s_lshl_b32 s100, s79, 2
	v_add_u32_e32 v161, s100, v145
	v_xor_b32_e32 v161, v161, v160
	v_lshlrev_b32_e32 v161, 3, v161
	v_lshl_add_u32 v161, v144, 8, v161
	s_lshl_b32 s100, s62, 13
	s_add_i32 s100, s100, 49152
	v_add_u32_e32 v161, s100, v161
	v_add_u32_e32 v167, 98304, v161
	v_xor_b32_e32 v162, v144, v145
	v_lshlrev_b32_e32 v162, 4, v162
	s_lshl_b32 s101, s79, 11
	s_add_i32 s101, s101, s100
	v_lshl_add_u32 v163, v145, 8, s101
	v_add_u32_e32 v164, v163, v162
	v_or_b32_e32 v165, 4, v145
	v_xor_b32_e32 v165, v144, v165
	v_lshl_add_u32 v165, v165, 4, v163
	v_add_u32_e32 v174, 98304, v164
	v_add_u32_e32 v175, 98304, v165
	v_sub_u32_e32 v166, v148, v144
	s_lshl_b32 s101, s79, 3
	v_add3_u32 v166, v166, s101, v145
	v_mov_b64_e32 v[170:171], s[6:7]
	v_mad_u64_u32 v[168:169], s[24:25], v166, s47, v[170:171]
	s_lshl_b32 s101, s79, 5
	v_subrev_u32_e32 v172, s101, v142
	v_lshlrev_b32_e32 v173, 3, v145
	v_sub_u32_e32 v172, v172, v173
	v_lshl_add_u32 v172, v144, 4, v172
	v_mov_b32_e32 v173, 0
	v_lshl_add_u64 v[168:169], v[168:169], 0, v[172:173]
	s_mov_b32 s101, 0
	ds_write_b64 v161, v[122:123] offset:0
	ds_write_b64 v161, v[114:115] offset:128
	ds_write_b64 v161, v[106:107] offset:4096
	ds_write_b64 v161, v[98:99] offset:4224
	v_mul_f32_e32 v152, 0xbfb8aa3b, v92
	v_mul_f32_e32 v153, 0xbfb8aa3b, v93
	v_mul_f32_e32 v154, 0xbfb8aa3b, v94
	v_mul_f32_e32 v155, 0xbfb8aa3b, v95
	v_mul_f32_e32 v156, 0xbfb8aa3b, v84
	v_mul_f32_e32 v157, 0xbfb8aa3b, v85
	v_mul_f32_e32 v158, 0xbfb8aa3b, v86
	v_mul_f32_e32 v159, 0xbfb8aa3b, v87
	v_exp_f32_e32 v152, v152
	v_exp_f32_e32 v153, v153
	v_exp_f32_e32 v154, v154
	v_exp_f32_e32 v155, v155
	v_exp_f32_e32 v156, v156
	v_exp_f32_e32 v157, v157
	v_exp_f32_e32 v158, v158
	v_exp_f32_e32 v159, v159
	v_add_f32_e32 v152, 1.0, v152
	v_add_f32_e32 v153, 1.0, v153
	v_add_f32_e32 v154, 1.0, v154
	v_add_f32_e32 v155, 1.0, v155
	v_add_f32_e32 v156, 1.0, v156
	v_add_f32_e32 v157, 1.0, v157
	v_add_f32_e32 v158, 1.0, v158
	v_add_f32_e32 v159, 1.0, v159
	v_rcp_f32_e32 v152, v152
	v_rcp_f32_e32 v153, v153
	v_rcp_f32_e32 v154, v154
	v_rcp_f32_e32 v155, v155
	v_rcp_f32_e32 v156, v156
	v_rcp_f32_e32 v157, v157
	v_rcp_f32_e32 v158, v158
	v_rcp_f32_e32 v159, v159
	v_mul_f32_e32 v152, v92, v152
	v_mul_f32_e32 v153, v93, v153
	v_mul_f32_e32 v154, v94, v154
	v_mul_f32_e32 v155, v95, v155
	v_mul_f32_e32 v156, v84, v156
	v_mul_f32_e32 v157, v85, v157
	v_mul_f32_e32 v158, v86, v158
	v_mul_f32_e32 v159, v87, v159
	v_mul_f32_e32 v88, v88, v152
	v_mul_f32_e32 v89, v89, v153
	v_mul_f32_e32 v90, v90, v154
	v_mul_f32_e32 v91, v91, v155
	v_mul_f32_e32 v80, v80, v156
	v_mul_f32_e32 v81, v81, v157
	v_mul_f32_e32 v82, v82, v158
	v_mul_f32_e32 v83, v83, v159
	v_cvt_pk_bf16_f32 v88, v88, v89
	v_cvt_pk_bf16_f32 v89, v90, v91
	v_cvt_pk_bf16_f32 v80, v80, v81
	v_cvt_pk_bf16_f32 v81, v82, v83
	v_mul_f32_e32 v152, 0xbfb8aa3b, v76
	v_mul_f32_e32 v153, 0xbfb8aa3b, v77
	v_mul_f32_e32 v154, 0xbfb8aa3b, v78
	v_mul_f32_e32 v155, 0xbfb8aa3b, v79
	v_mul_f32_e32 v156, 0xbfb8aa3b, v68
	v_mul_f32_e32 v157, 0xbfb8aa3b, v69
	v_mul_f32_e32 v158, 0xbfb8aa3b, v70
	v_mul_f32_e32 v159, 0xbfb8aa3b, v71
	v_exp_f32_e32 v152, v152
	v_exp_f32_e32 v153, v153
	v_exp_f32_e32 v154, v154
	v_exp_f32_e32 v155, v155
	v_exp_f32_e32 v156, v156
	v_exp_f32_e32 v157, v157
	v_exp_f32_e32 v158, v158
	v_exp_f32_e32 v159, v159
	v_add_f32_e32 v152, 1.0, v152
	v_add_f32_e32 v153, 1.0, v153
	v_add_f32_e32 v154, 1.0, v154
	v_add_f32_e32 v155, 1.0, v155
	v_add_f32_e32 v156, 1.0, v156
	v_add_f32_e32 v157, 1.0, v157
	v_add_f32_e32 v158, 1.0, v158
	v_add_f32_e32 v159, 1.0, v159
	v_rcp_f32_e32 v152, v152
	v_rcp_f32_e32 v153, v153
	v_rcp_f32_e32 v154, v154
	v_rcp_f32_e32 v155, v155
	v_rcp_f32_e32 v156, v156
	v_rcp_f32_e32 v157, v157
	v_rcp_f32_e32 v158, v158
	v_rcp_f32_e32 v159, v159
	v_mul_f32_e32 v152, v76, v152
	v_mul_f32_e32 v153, v77, v153
	v_mul_f32_e32 v154, v78, v154
	v_mul_f32_e32 v155, v79, v155
	v_mul_f32_e32 v156, v68, v156
	v_mul_f32_e32 v157, v69, v157
	v_mul_f32_e32 v158, v70, v158
	v_mul_f32_e32 v159, v71, v159
	v_mul_f32_e32 v72, v72, v152
	v_mul_f32_e32 v73, v73, v153
	v_mul_f32_e32 v74, v74, v154
	v_mul_f32_e32 v75, v75, v155
	v_mul_f32_e32 v64, v64, v156
	v_mul_f32_e32 v65, v65, v157
	v_mul_f32_e32 v66, v66, v158
	v_mul_f32_e32 v67, v67, v159
	v_cvt_pk_bf16_f32 v72, v72, v73
	v_cvt_pk_bf16_f32 v73, v74, v75
	v_cvt_pk_bf16_f32 v64, v64, v65
	v_cvt_pk_bf16_f32 v65, v66, v67
	s_waitcnt lgkmcnt(0)
	s_barrier
	ds_read_b128 v[176:179], v164
	ds_read_b128 v[180:183], v165 offset:1024
	s_waitcnt lgkmcnt(1)
	global_store_dwordx4 v[168:169], v[176:179], off
	s_mov_b32 s100, 22528
	v_lshl_add_u64 v[168:169], v[168:169], 0, s[100:101]
	s_waitcnt lgkmcnt(0)
	global_store_dwordx4 v[168:169], v[180:183], off
	s_mov_b32 s100, 157696
	v_lshl_add_u64 v[168:169], v[168:169], 0, s[100:101]
	s_nop 1
	ds_write_b64 v167, v[88:89] offset:0
	ds_write_b64 v167, v[80:81] offset:128
	ds_write_b64 v167, v[72:73] offset:4096
	ds_write_b64 v167, v[64:65] offset:4224
	v_mul_f32_e32 v152, 0xbfb8aa3b, v60
	v_mul_f32_e32 v153, 0xbfb8aa3b, v61
	v_mul_f32_e32 v154, 0xbfb8aa3b, v62
	v_mul_f32_e32 v155, 0xbfb8aa3b, v63
	v_mul_f32_e32 v156, 0xbfb8aa3b, v52
	v_mul_f32_e32 v157, 0xbfb8aa3b, v53
	v_mul_f32_e32 v158, 0xbfb8aa3b, v54
	v_mul_f32_e32 v159, 0xbfb8aa3b, v55
	v_exp_f32_e32 v152, v152
	v_exp_f32_e32 v153, v153
	v_exp_f32_e32 v154, v154
	v_exp_f32_e32 v155, v155
	v_exp_f32_e32 v156, v156
	v_exp_f32_e32 v157, v157
	v_exp_f32_e32 v158, v158
	v_exp_f32_e32 v159, v159
	v_add_f32_e32 v152, 1.0, v152
	v_add_f32_e32 v153, 1.0, v153
	v_add_f32_e32 v154, 1.0, v154
	v_add_f32_e32 v155, 1.0, v155
	v_add_f32_e32 v156, 1.0, v156
	v_add_f32_e32 v157, 1.0, v157
	v_add_f32_e32 v158, 1.0, v158
	v_add_f32_e32 v159, 1.0, v159
	v_rcp_f32_e32 v152, v152
	v_rcp_f32_e32 v153, v153
	v_rcp_f32_e32 v154, v154
	v_rcp_f32_e32 v155, v155
	v_rcp_f32_e32 v156, v156
	v_rcp_f32_e32 v157, v157
	v_rcp_f32_e32 v158, v158
	v_rcp_f32_e32 v159, v159
	v_mul_f32_e32 v152, v60, v152
	v_mul_f32_e32 v153, v61, v153
	v_mul_f32_e32 v154, v62, v154
	v_mul_f32_e32 v155, v63, v155
	v_mul_f32_e32 v156, v52, v156
	v_mul_f32_e32 v157, v53, v157
	v_mul_f32_e32 v158, v54, v158
	v_mul_f32_e32 v159, v55, v159
	v_mul_f32_e32 v56, v56, v152
	v_mul_f32_e32 v57, v57, v153
	v_mul_f32_e32 v58, v58, v154
	v_mul_f32_e32 v59, v59, v155
	v_mul_f32_e32 v48, v48, v156
	v_mul_f32_e32 v49, v49, v157
	v_mul_f32_e32 v50, v50, v158
	v_mul_f32_e32 v51, v51, v159
	v_cvt_pk_bf16_f32 v56, v56, v57
	v_cvt_pk_bf16_f32 v57, v58, v59
	v_cvt_pk_bf16_f32 v48, v48, v49
	v_cvt_pk_bf16_f32 v49, v50, v51
	v_mul_f32_e32 v152, 0xbfb8aa3b, v44
	v_mul_f32_e32 v153, 0xbfb8aa3b, v45
	v_mul_f32_e32 v154, 0xbfb8aa3b, v46
	v_mul_f32_e32 v155, 0xbfb8aa3b, v47
	v_mul_f32_e32 v156, 0xbfb8aa3b, v36
	v_mul_f32_e32 v157, 0xbfb8aa3b, v37
	v_mul_f32_e32 v158, 0xbfb8aa3b, v38
	v_mul_f32_e32 v159, 0xbfb8aa3b, v39
	v_exp_f32_e32 v152, v152
	v_exp_f32_e32 v153, v153
	v_exp_f32_e32 v154, v154
	v_exp_f32_e32 v155, v155
	v_exp_f32_e32 v156, v156
	v_exp_f32_e32 v157, v157
	v_exp_f32_e32 v158, v158
	v_exp_f32_e32 v159, v159
	v_add_f32_e32 v152, 1.0, v152
	v_add_f32_e32 v153, 1.0, v153
	v_add_f32_e32 v154, 1.0, v154
	v_add_f32_e32 v155, 1.0, v155
	v_add_f32_e32 v156, 1.0, v156
	v_add_f32_e32 v157, 1.0, v157
	v_add_f32_e32 v158, 1.0, v158
	v_add_f32_e32 v159, 1.0, v159
	v_rcp_f32_e32 v152, v152
	v_rcp_f32_e32 v153, v153
	v_rcp_f32_e32 v154, v154
	v_rcp_f32_e32 v155, v155
	v_rcp_f32_e32 v156, v156
	v_rcp_f32_e32 v157, v157
	v_rcp_f32_e32 v158, v158
	v_rcp_f32_e32 v159, v159
	v_mul_f32_e32 v152, v44, v152
	v_mul_f32_e32 v153, v45, v153
	v_mul_f32_e32 v154, v46, v154
	v_mul_f32_e32 v155, v47, v155
	v_mul_f32_e32 v156, v36, v156
	v_mul_f32_e32 v157, v37, v157
	v_mul_f32_e32 v158, v38, v158
	v_mul_f32_e32 v159, v39, v159
	v_mul_f32_e32 v40, v40, v152
	v_mul_f32_e32 v41, v41, v153
	v_mul_f32_e32 v42, v42, v154
	v_mul_f32_e32 v43, v43, v155
	v_mul_f32_e32 v32, v32, v156
	v_mul_f32_e32 v33, v33, v157
	v_mul_f32_e32 v34, v34, v158
	v_mul_f32_e32 v35, v35, v159
	v_cvt_pk_bf16_f32 v40, v40, v41
	v_cvt_pk_bf16_f32 v41, v42, v43
	v_cvt_pk_bf16_f32 v32, v32, v33
	v_cvt_pk_bf16_f32 v33, v34, v35
	s_waitcnt lgkmcnt(0)
	s_barrier
	ds_read_b128 v[176:179], v174
	ds_read_b128 v[180:183], v175 offset:1024
	s_waitcnt lgkmcnt(1)
	global_store_dwordx4 v[168:169], v[176:179], off
	s_mov_b32 s100, 22528
	v_lshl_add_u64 v[168:169], v[168:169], 0, s[100:101]
	s_waitcnt lgkmcnt(0)
	global_store_dwordx4 v[168:169], v[180:183], off
	s_mov_b32 s100, 518144
	v_lshl_add_u64 v[168:169], v[168:169], 0, s[100:101]
	s_nop 1
	ds_write_b64 v161, v[56:57] offset:0
	ds_write_b64 v161, v[48:49] offset:128
	ds_write_b64 v161, v[40:41] offset:4096
	ds_write_b64 v161, v[32:33] offset:4224
	v_mul_f32_e32 v152, 0xbfb8aa3b, v28
	v_mul_f32_e32 v153, 0xbfb8aa3b, v29
	v_mul_f32_e32 v154, 0xbfb8aa3b, v30
	v_mul_f32_e32 v155, 0xbfb8aa3b, v31
	v_mul_f32_e32 v156, 0xbfb8aa3b, v20
	v_mul_f32_e32 v157, 0xbfb8aa3b, v21
	v_mul_f32_e32 v158, 0xbfb8aa3b, v22
	v_mul_f32_e32 v159, 0xbfb8aa3b, v23
	v_exp_f32_e32 v152, v152
	v_exp_f32_e32 v153, v153
	v_exp_f32_e32 v154, v154
	v_exp_f32_e32 v155, v155
	v_exp_f32_e32 v156, v156
	v_exp_f32_e32 v157, v157
	v_exp_f32_e32 v158, v158
	v_exp_f32_e32 v159, v159
	v_add_f32_e32 v152, 1.0, v152
	v_add_f32_e32 v153, 1.0, v153
	v_add_f32_e32 v154, 1.0, v154
	v_add_f32_e32 v155, 1.0, v155
	v_add_f32_e32 v156, 1.0, v156
	v_add_f32_e32 v157, 1.0, v157
	v_add_f32_e32 v158, 1.0, v158
	v_add_f32_e32 v159, 1.0, v159
	v_rcp_f32_e32 v152, v152
	v_rcp_f32_e32 v153, v153
	v_rcp_f32_e32 v154, v154
	v_rcp_f32_e32 v155, v155
	v_rcp_f32_e32 v156, v156
	v_rcp_f32_e32 v157, v157
	v_rcp_f32_e32 v158, v158
	v_rcp_f32_e32 v159, v159
	v_mul_f32_e32 v152, v28, v152
	v_mul_f32_e32 v153, v29, v153
	v_mul_f32_e32 v154, v30, v154
	v_mul_f32_e32 v155, v31, v155
	v_mul_f32_e32 v156, v20, v156
	v_mul_f32_e32 v157, v21, v157
	v_mul_f32_e32 v158, v22, v158
	v_mul_f32_e32 v159, v23, v159
	v_mul_f32_e32 v24, v24, v152
	v_mul_f32_e32 v25, v25, v153
	v_mul_f32_e32 v26, v26, v154
	v_mul_f32_e32 v27, v27, v155
	v_mul_f32_e32 v16, v16, v156
	v_mul_f32_e32 v17, v17, v157
	v_mul_f32_e32 v18, v18, v158
	v_mul_f32_e32 v19, v19, v159
	v_cvt_pk_bf16_f32 v24, v24, v25
	v_cvt_pk_bf16_f32 v25, v26, v27
	v_cvt_pk_bf16_f32 v16, v16, v17
	v_cvt_pk_bf16_f32 v17, v18, v19
	s_mov_b64 s[24:25], -1
	v_mul_f32_e32 v152, 0xbfb8aa3b, v12
	v_mul_f32_e32 v153, 0xbfb8aa3b, v13
	v_mul_f32_e32 v154, 0xbfb8aa3b, v14
	v_mul_f32_e32 v155, 0xbfb8aa3b, v15
	v_mul_f32_e32 v156, 0xbfb8aa3b, v4
	v_mul_f32_e32 v157, 0xbfb8aa3b, v5
	v_mul_f32_e32 v158, 0xbfb8aa3b, v6
	v_mul_f32_e32 v159, 0xbfb8aa3b, v7
	v_exp_f32_e32 v152, v152
	v_exp_f32_e32 v153, v153
	v_exp_f32_e32 v154, v154
	v_exp_f32_e32 v155, v155
	v_exp_f32_e32 v156, v156
	v_exp_f32_e32 v157, v157
	v_exp_f32_e32 v158, v158
	v_exp_f32_e32 v159, v159
	v_add_f32_e32 v152, 1.0, v152
	v_add_f32_e32 v153, 1.0, v153
	v_add_f32_e32 v154, 1.0, v154
	v_add_f32_e32 v155, 1.0, v155
	v_add_f32_e32 v156, 1.0, v156
	v_add_f32_e32 v157, 1.0, v157
	v_add_f32_e32 v158, 1.0, v158
	v_add_f32_e32 v159, 1.0, v159
	v_rcp_f32_e32 v152, v152
	v_rcp_f32_e32 v153, v153
	v_rcp_f32_e32 v154, v154
	v_rcp_f32_e32 v155, v155
	v_rcp_f32_e32 v156, v156
	v_rcp_f32_e32 v157, v157
	v_rcp_f32_e32 v158, v158
	v_rcp_f32_e32 v159, v159
	v_mul_f32_e32 v152, v12, v152
	v_mul_f32_e32 v153, v13, v153
	v_mul_f32_e32 v154, v14, v154
	v_mul_f32_e32 v155, v15, v155
	v_mul_f32_e32 v156, v4, v156
	v_mul_f32_e32 v157, v5, v157
	v_mul_f32_e32 v158, v6, v158
	v_mul_f32_e32 v159, v7, v159
	v_mul_f32_e32 v8, v8, v152
	v_mul_f32_e32 v9, v9, v153
	v_mul_f32_e32 v10, v10, v154
	v_mul_f32_e32 v11, v11, v155
	v_mul_f32_e32 v0, v0, v156
	v_mul_f32_e32 v1, v1, v157
	v_mul_f32_e32 v2, v2, v158
	v_mul_f32_e32 v3, v3, v159
	v_cvt_pk_bf16_f32 v8, v8, v9
	v_cvt_pk_bf16_f32 v9, v10, v11
	v_cvt_pk_bf16_f32 v0, v0, v1
	v_cvt_pk_bf16_f32 v1, v2, v3
	s_waitcnt lgkmcnt(0)
	s_barrier
	ds_read_b128 v[176:179], v164
	ds_read_b128 v[180:183], v165 offset:1024
	s_waitcnt lgkmcnt(1)
	global_store_dwordx4 v[168:169], v[176:179], off
	s_mov_b32 s100, 22528
	v_lshl_add_u64 v[168:169], v[168:169], 0, s[100:101]
	s_waitcnt lgkmcnt(0)
	global_store_dwordx4 v[168:169], v[180:183], off
	s_mov_b32 s100, 157696
	v_lshl_add_u64 v[168:169], v[168:169], 0, s[100:101]
	s_nop 1
	ds_write_b64 v167, v[24:25] offset:0
	ds_write_b64 v167, v[16:17] offset:128
	ds_write_b64 v167, v[8:9] offset:4096
	ds_write_b64 v167, v[0:1] offset:4224
	s_waitcnt lgkmcnt(0)
	s_barrier
	ds_read_b128 v[176:179], v174
	ds_read_b128 v[180:183], v175 offset:1024
	s_waitcnt lgkmcnt(1)
	global_store_dwordx4 v[168:169], v[176:179], off
	s_mov_b32 s100, 22528
	v_lshl_add_u64 v[168:169], v[168:169], 0, s[100:101]
	s_waitcnt lgkmcnt(0)
	global_store_dwordx4 v[168:169], v[180:183], off
	s_nop 1
	s_cbranch_vccnz .LBB0_729
	s_andn2_b64 vcc, exec, s[4:5]
	s_cbranch_vccnz .LBB0_728
	s_barrier
	s_branch .LBB0_728
